# final norm de-serialised: a row's twelve plane/gain loads requested together, output stores not waited on inside the row; on top of the combination
# baseline (speedup 1.0000x reference)
.LBB11_3038:
	s_cmpk_lt_i32 s18, 0x400
	s_cselect_b64 s[2:3], -1, 0
	s_or_b64 s[8:9], s[0:1], s[2:3]
	s_andn2_b64 vcc, exec, s[8:9]
	s_cbranch_vccnz .LBB11_3037
	s_and_b64 s[2:3], s[2:3], exec
	s_cselect_b32 s2, s19, 0x3c00
	s_add_i32 s12, s18, s2
	s_ashr_i32 s3, s2, 31
	s_add_u32 s2, s18, s2
	s_addc_u32 s3, s6, s3
	s_lshl_b64 s[8:9], s[2:3], 2
	s_add_u32 s8, s4, s8
	s_addc_u32 s9, s5, s9
	global_load_dword v22, v6, s[8:9]
	s_load_dwordx4 s[8:11], s[16:17], 0x128
	s_add_i32 s14, s12, 0xffffc000
	s_cmpk_lt_i32 s12, 0x4000
	s_cselect_b32 s12, s2, s14
	s_cselect_b32 s14, 0, 0x4000000
	s_cselect_b32 s13, s3, 0
	s_waitcnt lgkmcnt(0)
	s_add_u32 s14, s10, s14
	s_addc_u32 s15, s11, 0
	s_lshl_b64 s[10:11], s[12:13], 12
	s_add_u32 s10, s14, s10
	s_addc_u32 s11, s15, s11
	s_lshl_b64 s[2:3], s[2:3], 11
	v_lshl_add_u64 v[12:13], v[0:1], 0, s[2:3]
	v_lshl_add_u64 v[16:17], v[2:3], 0, s[2:3]
	global_load_dwordx2 v[14:15], v[12:13], off
	global_load_dwordx2 v[18:19], v[16:17], off
	v_lshl_add_u64 v[20:21], s[8:9], 0, v[4:5]
	global_load_dwordx4 v[8:11], v[20:21], off
	global_load_dwordx2 v[30:31], v[12:13], off offset:512
	global_load_dwordx2 v[36:37], v[16:17], off offset:512
	global_load_dwordx4 v[42:45], v[20:21], off offset:1024
	global_load_dwordx2 v[32:33], v[12:13], off offset:1024
	global_load_dwordx2 v[38:39], v[16:17], off offset:1024
	global_load_dwordx4 v[46:49], v[20:21], off offset:2048
	global_load_dwordx2 v[34:35], v[12:13], off offset:1536
	global_load_dwordx2 v[40:41], v[16:17], off offset:1536
	global_load_dwordx4 v[50:53], v[20:21], off offset:3072
	s_waitcnt vmcnt(12)
	v_fmamk_f32 v22, v22, 0x3a800000, v7
	v_mul_f32_e32 v23, 0x4b800000, v22
	v_cmp_gt_f32_e32 vcc, s7, v22
	s_waitcnt vmcnt(11)
	v_lshlrev_b32_e32 v24, 16, v14
	v_cndmask_b32_e32 v22, v22, v23, vcc
	v_rsq_f32_e32 v28, v22
	v_and_b32_e32 v25, 0xffff0000, v14
	s_waitcnt vmcnt(10)
	v_lshlrev_b32_e32 v26, 16, v18
	v_and_b32_e32 v27, 0xffff0000, v18
	v_mul_f32_e32 v29, 0x45800000, v28
	v_lshlrev_b32_e32 v14, 16, v15
	v_and_b32_e32 v15, 0xffff0000, v15
	v_lshlrev_b32_e32 v18, 16, v19
	v_and_b32_e32 v19, 0xffff0000, v19
	v_cndmask_b32_e32 v28, v28, v29, vcc
	v_pk_add_f32 v[24:25], v[24:25], v[26:27]
	v_pk_add_f32 v[14:15], v[14:15], v[18:19]
	v_pk_mul_f32 v[18:19], v[28:29], v[24:25] op_sel_hi:[0,1]
	v_pk_mul_f32 v[14:15], v[28:29], v[14:15] op_sel_hi:[0,1]
	v_lshl_add_u64 v[22:23], s[10:11], 0, v[4:5]
	s_waitcnt vmcnt(9)
	v_pk_mul_f32 v[10:11], v[10:11], v[14:15]
	v_pk_mul_f32 v[8:9], v[8:9], v[18:19]
	global_store_dwordx4 v[22:23], v[8:11], off nt
	s_waitcnt vmcnt(9)
	v_lshlrev_b32_e32 v24, 16, v30
	v_and_b32_e32 v25, 0xffff0000, v30
	s_waitcnt vmcnt(8)
	v_lshlrev_b32_e32 v26, 16, v36
	v_and_b32_e32 v27, 0xffff0000, v36
	v_lshlrev_b32_e32 v30, 16, v31
	v_and_b32_e32 v31, 0xffff0000, v31
	v_lshlrev_b32_e32 v36, 16, v37
	v_and_b32_e32 v37, 0xffff0000, v37
	v_pk_add_f32 v[24:25], v[24:25], v[26:27]
	v_pk_add_f32 v[30:31], v[30:31], v[36:37]
	v_pk_mul_f32 v[36:37], v[28:29], v[24:25] op_sel_hi:[0,1]
	v_pk_mul_f32 v[30:31], v[28:29], v[30:31] op_sel_hi:[0,1]
	s_waitcnt vmcnt(7)
	v_pk_mul_f32 v[44:45], v[44:45], v[30:31]
	v_pk_mul_f32 v[42:43], v[42:43], v[36:37]
	global_store_dwordx4 v[22:23], v[42:45], off offset:1024 nt
	s_waitcnt vmcnt(7)
	v_lshlrev_b32_e32 v24, 16, v32
	v_and_b32_e32 v25, 0xffff0000, v32
	s_waitcnt vmcnt(6)
	v_lshlrev_b32_e32 v26, 16, v38
	v_and_b32_e32 v27, 0xffff0000, v38
	v_lshlrev_b32_e32 v32, 16, v33
	v_and_b32_e32 v33, 0xffff0000, v33
	v_lshlrev_b32_e32 v38, 16, v39
	v_and_b32_e32 v39, 0xffff0000, v39
	v_pk_add_f32 v[24:25], v[24:25], v[26:27]
	v_pk_add_f32 v[32:33], v[32:33], v[38:39]
	v_pk_mul_f32 v[38:39], v[28:29], v[24:25] op_sel_hi:[0,1]
	v_pk_mul_f32 v[32:33], v[28:29], v[32:33] op_sel_hi:[0,1]
	s_waitcnt vmcnt(5)
	v_pk_mul_f32 v[48:49], v[48:49], v[32:33]
	v_pk_mul_f32 v[46:47], v[46:47], v[38:39]
	global_store_dwordx4 v[22:23], v[46:49], off offset:2048 nt
	s_waitcnt vmcnt(5)
	v_lshlrev_b32_e32 v12, 16, v34
	v_and_b32_e32 v13, 0xffff0000, v34
	s_waitcnt vmcnt(4)
	v_lshlrev_b32_e32 v16, 16, v40
	v_and_b32_e32 v17, 0xffff0000, v40
	v_lshlrev_b32_e32 v34, 16, v35
	v_and_b32_e32 v35, 0xffff0000, v35
	v_lshlrev_b32_e32 v40, 16, v41
	v_and_b32_e32 v41, 0xffff0000, v41
	v_pk_add_f32 v[12:13], v[12:13], v[16:17]
	v_pk_add_f32 v[34:35], v[34:35], v[40:41]
	v_pk_mul_f32 v[12:13], v[28:29], v[12:13] op_sel_hi:[0,1]
	v_pk_mul_f32 v[34:35], v[28:29], v[34:35] op_sel_hi:[0,1]
	s_waitcnt vmcnt(3)
	v_pk_mul_f32 v[52:53], v[52:53], v[34:35]
	v_pk_mul_f32 v[50:51], v[50:51], v[12:13]
	global_store_dwordx4 v[22:23], v[50:53], off offset:3072 nt
	s_branch .LBB11_3037
